# codepf: waves 1..7 touch the next phase's code (one dword per 64 B line, 28 KiB) while the block waits in the grid barrier; rest = v95
# speedup vs baseline: 1.0121x; 1.0075x over previous
; #define RUN_PH(k) if (ph0 <= (k) && (k) < ph1) { if ((k) != ph0) xcd_barrier(xb); run_phase<(k)>(kp, shm); }
; __device__ __forceinline__ void xcd_barrier(const XcdBarrier& b) {
;     asm volatile("s_waitcnt vmcnt(0)" ::: "memory");
;     __syncthreads();
;     if (threadIdx.x == 0) {
;         unsigned* bar = b.bar;
;         __builtin_amdgcn_s_waitcnt(0);
;         unsigned nloc = b.st[0], nx = b.st[1];
;         if (nloc == 0u) { xcd_barrier_complete(bar, b.x, nloc, nx); b.st[0] = nloc; b.st[1] = nx; }
; __global__ void __launch_bounds__(512, 2) mega(Params P, int ph0, int ph1) {
;     ...
;     RUN_PH(0) RUN_PH(1) RUN_PH(2) RUN_PH(3) RUN_PH(4) RUN_PH(5) RUN_PH(6) RUN_PH(7) RUN_PH(8) RUN_PH(9)
;     RUN_PH(10) RUN_PH(11) RUN_PH(12) RUN_PH(13) RUN_PH(14) RUN_PH(15) RUN_PH(16) RUN_PH(17)
.LBB0_5:
	s_or_b64 exec, exec, s[4:5]
	s_load_dwordx2 s[94:95], s[86:87], 0xd8
	s_waitcnt lgkmcnt(0)
	s_cmp_gt_i32 s94, 0
	s_cselect_b64 s[0:1], -1, 0
	s_cmp_lt_i32 s95, 1
	s_cselect_b64 s[2:3], -1, 0
	s_or_b64 s[0:1], s[0:1], s[2:3]
	s_and_b64 vcc, exec, s[0:1]
	s_cbranch_vccnz .LBB0_258
	s_cmp_eq_u32 s94, 0
	s_cbranch_scc1 .LBB0_60
	s_waitcnt vmcnt(0)
	v_cmp_lt_u32_e32 vcc, 63, v0
	s_and_saveexec_b64 s[0:1], vcc
	s_getpc_b64 s[2:3]
	v_lshlrev_b32_e32 v1, 6, v0
	global_load_dword v1, v1, s[2:3] offset:-4096
	s_mov_b64 exec, s[0:1]
	s_nop 0
	s_barrier
	s_and_saveexec_b64 s[4:5], s[92:93]
	s_cbranch_execz .LBB0_59
	v_mov_b32_e32 v1, 0
	s_waitcnt vmcnt(0) expcnt(0) lgkmcnt(0)
	ds_read_b32 v3, v1
	ds_read_b32 v2, v1 offset:4
	s_waitcnt lgkmcnt(1)
	v_cmp_ne_u32_e32 vcc, 0, v3
	s_cbranch_vccnz .LBB0_23
	s_add_u32 s6, s88, 0x2e9d8200
	s_addc_u32 s7, s89, 0
	s_add_u32 s8, s88, 0x2e9d8400
	s_addc_u32 s9, s89, 0
	s_add_u32 s12, s88, 0x2e9d8500
	s_addc_u32 s13, s89, 0
	s_add_u32 s14, s88, 0x2e9d8600
	s_addc_u32 s15, s89, 0
	s_add_u32 s16, s88, 0x2e9d8700
	s_addc_u32 s17, s89, 0
	s_add_u32 s18, s88, 0x2e9d8800
	s_addc_u32 s19, s89, 0
	s_add_u32 s20, s88, 0x2e9d8900
	s_addc_u32 s21, s89, 0
	s_add_u32 s22, s88, 0x2e9d8a00
	s_addc_u32 s23, s89, 0
	s_add_u32 s24, s88, 0x2e9d8b00
	s_addc_u32 s25, s89, 0
	s_add_u32 s26, s88, 0x2e9d8c00
	s_addc_u32 s27, s89, 0
	s_add_u32 s28, s88, 0x2e9d8d00
	s_addc_u32 s29, s89, 0
	s_add_u32 s34, s88, 0x2e9d8e00
	s_addc_u32 s35, s89, 0
	s_add_u32 s36, s88, 0x2e9d8f00
	s_addc_u32 s37, s89, 0
	s_add_u32 s38, s88, 0x2e9d9000
	s_addc_u32 s39, s89, 0
	s_load_dwordx2 s[0:1], s[86:87], 0xe0
	s_load_dword s2, s[86:87], 0xe8
	s_add_u32 s40, s88, 0x2e9d9100
	s_addc_u32 s41, s89, 0
	s_add_u32 s42, s88, 0x2e9d9200
	s_addc_u32 s43, s89, 0
	s_waitcnt lgkmcnt(0)
	s_mul_i32 s0, s1, s0
	s_add_u32 s44, s88, 0x2e9d9300
	s_mul_i32 s0, s0, s2
	s_addc_u32 s45, s89, 0
	s_mov_b32 s1, 1
	s_branch .LBB0_11

; __device__ __forceinline__ unsigned xb_ld(unsigned* p)              { return __hip_atomic_load(p, __ATOMIC_RELAXED, __HIP_MEMORY_SCOPE_AGENT); }
; #define XB_SPIN(cond, bar) do { unsigned _sp = 0; while (cond) {   \
;     if ((++_sp & 255u) == 0u) { if (xb_ld(&(bar)[XB_TMO])) break; if (_sp > XB_SPIN_CAP) { atomicAdd(&(bar)[XB_TMO], 1u); break; } } } } while (0)
; __device__ __forceinline__ void xcd_barrier(const XcdBarrier& b) {
;     ...
;         } else {
;             XB_SPIN(xb_ld(&bar[XB_XGEN(b.x)]) == gen, bar);
;             __builtin_amdgcn_fence(__ATOMIC_ACQUIRE, "agent");
;             asm volatile("s_waitcnt vmcnt(0)" ::: "memory");
;         }
;     }
;     __syncthreads();
.LBB0_59:
	s_or_b64 exec, exec, s[4:5]
	s_waitcnt vmcnt(0) lgkmcnt(0)
	s_barrier

; #define RUN_PH(k) if (ph0 <= (k) && (k) < ph1) { if ((k) != ph0) xcd_barrier(xb); run_phase<(k)>(kp, shm); }
; __device__ __forceinline__ void xcd_barrier(const XcdBarrier& b) {
;     asm volatile("s_waitcnt vmcnt(0)" ::: "memory");
;     __syncthreads();
;     if (threadIdx.x == 0) {
;         unsigned* bar = b.bar;
;         __builtin_amdgcn_s_waitcnt(0);
;         unsigned nloc = b.st[0], nx = b.st[1];
;         if (nloc == 0u) { xcd_barrier_complete(bar, b.x, nloc, nx); b.st[0] = nloc; b.st[1] = nx; }
; __global__ void __launch_bounds__(512, 2) mega(Params P, int ph0, int ph1) {
;     ...
;     RUN_PH(0) RUN_PH(1) RUN_PH(2) RUN_PH(3) RUN_PH(4) RUN_PH(5) RUN_PH(6) RUN_PH(7) RUN_PH(8) RUN_PH(9)
;     RUN_PH(10) RUN_PH(11) RUN_PH(12) RUN_PH(13) RUN_PH(14) RUN_PH(15) RUN_PH(16) RUN_PH(17)
.LBB0_258:
	s_cmp_gt_i32 s94, 1
	s_cselect_b64 s[0:1], -1, 0
	s_cmp_lt_i32 s95, 2
	s_cselect_b64 s[2:3], -1, 0
	s_or_b64 s[0:1], s[0:1], s[2:3]
	s_and_b64 vcc, exec, s[0:1]
	s_cbranch_vccnz .LBB0_319
	s_cmp_eq_u32 s94, 1
	s_cbranch_scc1 .LBB0_313
	s_waitcnt vmcnt(0)
	v_cmp_lt_u32_e32 vcc, 63, v0
	s_and_saveexec_b64 s[0:1], vcc
	s_getpc_b64 s[2:3]
	v_lshlrev_b32_e32 v1, 6, v0
	global_load_dword v1, v1, s[2:3] offset:-4096
	s_mov_b64 exec, s[0:1]
	s_nop 0
	s_barrier
	s_and_saveexec_b64 s[4:5], s[92:93]
	s_cbranch_execz .LBB0_312
	v_mov_b32_e32 v1, 0
	s_waitcnt vmcnt(0) expcnt(0) lgkmcnt(0)
	ds_read_b32 v3, v1
	ds_read_b32 v2, v1 offset:4
	s_waitcnt lgkmcnt(1)
	v_cmp_ne_u32_e32 vcc, 0, v3
	s_cbranch_vccnz .LBB0_276
	s_add_u32 s6, s88, 0x2e9d8200
	s_addc_u32 s7, s89, 0
	s_add_u32 s8, s88, 0x2e9d8400
	s_addc_u32 s9, s89, 0
	s_add_u32 s12, s88, 0x2e9d8500
	s_addc_u32 s13, s89, 0
	s_add_u32 s14, s88, 0x2e9d8600
	s_addc_u32 s15, s89, 0
	s_add_u32 s16, s88, 0x2e9d8700
	s_addc_u32 s17, s89, 0
	s_add_u32 s18, s88, 0x2e9d8800
	s_addc_u32 s19, s89, 0
	s_add_u32 s20, s88, 0x2e9d8900
	s_addc_u32 s21, s89, 0
	s_add_u32 s22, s88, 0x2e9d8a00
	s_addc_u32 s23, s89, 0
	s_add_u32 s24, s88, 0x2e9d8b00
	s_addc_u32 s25, s89, 0
	s_add_u32 s26, s88, 0x2e9d8c00
	s_addc_u32 s27, s89, 0
	s_add_u32 s28, s88, 0x2e9d8d00
	s_addc_u32 s29, s89, 0
	s_add_u32 s34, s88, 0x2e9d8e00
	s_addc_u32 s35, s89, 0
	s_add_u32 s36, s88, 0x2e9d8f00
	s_addc_u32 s37, s89, 0
	s_add_u32 s38, s88, 0x2e9d9000
	s_addc_u32 s39, s89, 0
	s_load_dwordx2 s[0:1], s[86:87], 0xe0
	s_load_dword s2, s[86:87], 0xe8
	s_add_u32 s40, s88, 0x2e9d9100
	s_addc_u32 s41, s89, 0
	s_add_u32 s42, s88, 0x2e9d9200
	s_addc_u32 s43, s89, 0
	s_waitcnt lgkmcnt(0)
	s_mul_i32 s0, s1, s0
	s_add_u32 s44, s88, 0x2e9d9300
	s_mul_i32 s0, s0, s2
	s_addc_u32 s45, s89, 0
	s_mov_b32 s1, 1
	s_branch .LBB0_264

; #define RUN_PH(k) if (ph0 <= (k) && (k) < ph1) { if ((k) != ph0) xcd_barrier(xb); run_phase<(k)>(kp, shm); }
; __device__ __forceinline__ void xcd_barrier(const XcdBarrier& b) {
;     asm volatile("s_waitcnt vmcnt(0)" ::: "memory");
;     __syncthreads();
;     if (threadIdx.x == 0) {
;         unsigned* bar = b.bar;
;         __builtin_amdgcn_s_waitcnt(0);
;         unsigned nloc = b.st[0], nx = b.st[1];
;         if (nloc == 0u) { xcd_barrier_complete(bar, b.x, nloc, nx); b.st[0] = nloc; b.st[1] = nx; }
; __global__ void __launch_bounds__(512, 2) mega(Params P, int ph0, int ph1) {
;     ...
;     RUN_PH(0) RUN_PH(1) RUN_PH(2) RUN_PH(3) RUN_PH(4) RUN_PH(5) RUN_PH(6) RUN_PH(7) RUN_PH(8) RUN_PH(9)
;     RUN_PH(10) RUN_PH(11) RUN_PH(12) RUN_PH(13) RUN_PH(14) RUN_PH(15) RUN_PH(16) RUN_PH(17)
.LBB0_319:
	s_cmp_gt_i32 s94, 2
	s_cselect_b64 s[0:1], -1, 0
	s_cmp_lt_i32 s95, 3
	s_cselect_b64 s[2:3], -1, 0
	s_or_b64 s[0:1], s[0:1], s[2:3]
	s_and_b64 vcc, exec, s[0:1]
	s_cbranch_vccnz .LBB0_436
	s_cmp_eq_u32 s94, 2
	s_cbranch_scc1 .LBB0_374
	s_waitcnt vmcnt(0)
	v_cmp_lt_u32_e32 vcc, 63, v0
	s_and_saveexec_b64 s[0:1], vcc
	s_getpc_b64 s[2:3]
	v_lshlrev_b32_e32 v1, 6, v0
	global_load_dword v1, v1, s[2:3] offset:-4096
	s_mov_b64 exec, s[0:1]
	s_nop 0
	s_barrier
	s_and_saveexec_b64 s[4:5], s[92:93]
	s_cbranch_execz .LBB0_373
	v_mov_b32_e32 v1, 0
	s_waitcnt vmcnt(0) expcnt(0) lgkmcnt(0)
	ds_read_b32 v3, v1
	ds_read_b32 v2, v1 offset:4
	s_waitcnt lgkmcnt(1)
	v_cmp_ne_u32_e32 vcc, 0, v3
	s_cbranch_vccnz .LBB0_337
	s_add_u32 s6, s88, 0x2e9d8200
	s_addc_u32 s7, s89, 0
	s_add_u32 s8, s88, 0x2e9d8400
	s_addc_u32 s9, s89, 0
	s_add_u32 s12, s88, 0x2e9d8500
	s_addc_u32 s13, s89, 0
	s_add_u32 s14, s88, 0x2e9d8600
	s_addc_u32 s15, s89, 0
	s_add_u32 s16, s88, 0x2e9d8700
	s_addc_u32 s17, s89, 0
	s_add_u32 s18, s88, 0x2e9d8800
	s_addc_u32 s19, s89, 0
	s_add_u32 s20, s88, 0x2e9d8900
	s_addc_u32 s21, s89, 0
	s_add_u32 s22, s88, 0x2e9d8a00
	s_addc_u32 s23, s89, 0
	s_add_u32 s24, s88, 0x2e9d8b00
	s_addc_u32 s25, s89, 0
	s_add_u32 s26, s88, 0x2e9d8c00
	s_addc_u32 s27, s89, 0
	s_add_u32 s28, s88, 0x2e9d8d00
	s_addc_u32 s29, s89, 0
	s_add_u32 s34, s88, 0x2e9d8e00
	s_addc_u32 s35, s89, 0
	s_add_u32 s36, s88, 0x2e9d8f00
	s_addc_u32 s37, s89, 0
	s_add_u32 s38, s88, 0x2e9d9000
	s_addc_u32 s39, s89, 0
	s_load_dwordx2 s[0:1], s[86:87], 0xe0
	s_load_dword s2, s[86:87], 0xe8
	s_add_u32 s40, s88, 0x2e9d9100
	s_addc_u32 s41, s89, 0
	s_add_u32 s42, s88, 0x2e9d9200
	s_addc_u32 s43, s89, 0
	s_waitcnt lgkmcnt(0)
	s_mul_i32 s0, s1, s0
	s_add_u32 s44, s88, 0x2e9d9300
	s_mul_i32 s0, s0, s2
	s_addc_u32 s45, s89, 0
	s_mov_b32 s1, 1
	s_branch .LBB0_325

; #define RUN_PH(k) if (ph0 <= (k) && (k) < ph1) { if ((k) != ph0) xcd_barrier(xb); run_phase<(k)>(kp, shm); }
; __device__ __forceinline__ void xcd_barrier(const XcdBarrier& b) {
;     asm volatile("s_waitcnt vmcnt(0)" ::: "memory");
;     __syncthreads();
;     if (threadIdx.x == 0) {
;         unsigned* bar = b.bar;
;         __builtin_amdgcn_s_waitcnt(0);
;         unsigned nloc = b.st[0], nx = b.st[1];
;         if (nloc == 0u) { xcd_barrier_complete(bar, b.x, nloc, nx); b.st[0] = nloc; b.st[1] = nx; }
; __global__ void __launch_bounds__(512, 2) mega(Params P, int ph0, int ph1) {
;     ...
;     RUN_PH(0) RUN_PH(1) RUN_PH(2) RUN_PH(3) RUN_PH(4) RUN_PH(5) RUN_PH(6) RUN_PH(7) RUN_PH(8) RUN_PH(9)
;     RUN_PH(10) RUN_PH(11) RUN_PH(12) RUN_PH(13) RUN_PH(14) RUN_PH(15) RUN_PH(16) RUN_PH(17)
.LBB0_436:
	s_cmp_gt_i32 s94, 3
	s_cselect_b64 s[0:1], -1, 0
	s_cmp_lt_i32 s95, 4
	s_cselect_b64 s[2:3], -1, 0
	s_or_b64 s[0:1], s[0:1], s[2:3]
	s_and_b64 vcc, exec, s[0:1]
	s_cbranch_vccnz .LBB0_508
	s_cmp_eq_u32 s94, 3
	s_cbranch_scc1 .LBB0_491
	s_waitcnt vmcnt(0)
	s_waitcnt vmcnt(0) lgkmcnt(0)
	v_cmp_lt_u32_e32 vcc, 63, v0
	s_and_saveexec_b64 s[0:1], vcc
	s_getpc_b64 s[2:3]
	v_lshlrev_b32_e32 v1, 6, v0
	global_load_dword v1, v1, s[2:3] offset:-4096
	s_mov_b64 exec, s[0:1]
	s_nop 0
	s_barrier
	s_and_saveexec_b64 s[4:5], s[92:93]
	s_cbranch_execz .LBB0_490
	v_mov_b32_e32 v1, 0
	s_waitcnt vmcnt(0) expcnt(0) lgkmcnt(0)
	ds_read_b32 v3, v1
	ds_read_b32 v2, v1 offset:4
	s_waitcnt lgkmcnt(1)
	v_cmp_ne_u32_e32 vcc, 0, v3
	s_cbranch_vccnz .LBB0_454
	s_add_u32 s6, s88, 0x2e9d8200
	s_addc_u32 s7, s89, 0
	s_add_u32 s8, s88, 0x2e9d8400
	s_addc_u32 s9, s89, 0
	s_add_u32 s12, s88, 0x2e9d8500
	s_addc_u32 s13, s89, 0
	s_add_u32 s14, s88, 0x2e9d8600
	s_addc_u32 s15, s89, 0
	s_add_u32 s16, s88, 0x2e9d8700
	s_addc_u32 s17, s89, 0
	s_add_u32 s18, s88, 0x2e9d8800
	s_addc_u32 s19, s89, 0
	s_add_u32 s20, s88, 0x2e9d8900
	s_addc_u32 s21, s89, 0
	s_add_u32 s22, s88, 0x2e9d8a00
	s_addc_u32 s23, s89, 0
	s_add_u32 s24, s88, 0x2e9d8b00
	s_addc_u32 s25, s89, 0
	s_add_u32 s26, s88, 0x2e9d8c00
	s_addc_u32 s27, s89, 0
	s_add_u32 s28, s88, 0x2e9d8d00
	s_addc_u32 s29, s89, 0
	s_add_u32 s34, s88, 0x2e9d8e00
	s_addc_u32 s35, s89, 0
	s_add_u32 s36, s88, 0x2e9d8f00
	s_addc_u32 s37, s89, 0
	s_add_u32 s38, s88, 0x2e9d9000
	s_addc_u32 s39, s89, 0
	s_load_dwordx2 s[0:1], s[86:87], 0xe0
	s_load_dword s2, s[86:87], 0xe8
	s_add_u32 s40, s88, 0x2e9d9100
	s_addc_u32 s41, s89, 0
	s_add_u32 s42, s88, 0x2e9d9200
	s_addc_u32 s43, s89, 0
	s_waitcnt lgkmcnt(0)
	s_mul_i32 s0, s1, s0
	s_add_u32 s44, s88, 0x2e9d9300
	s_mul_i32 s0, s0, s2
	s_addc_u32 s45, s89, 0
	s_mov_b32 s1, 1
	s_branch .LBB0_442

; #define RUN_PH(k) if (ph0 <= (k) && (k) < ph1) { if ((k) != ph0) xcd_barrier(xb); run_phase<(k)>(kp, shm); }
; __device__ __forceinline__ void xcd_barrier(const XcdBarrier& b) {
;     asm volatile("s_waitcnt vmcnt(0)" ::: "memory");
;     __syncthreads();
;     if (threadIdx.x == 0) {
;         unsigned* bar = b.bar;
;         __builtin_amdgcn_s_waitcnt(0);
;         unsigned nloc = b.st[0], nx = b.st[1];
;         if (nloc == 0u) { xcd_barrier_complete(bar, b.x, nloc, nx); b.st[0] = nloc; b.st[1] = nx; }
; __global__ void __launch_bounds__(512, 2) mega(Params P, int ph0, int ph1) {
;     ...
;     RUN_PH(0) RUN_PH(1) RUN_PH(2) RUN_PH(3) RUN_PH(4) RUN_PH(5) RUN_PH(6) RUN_PH(7) RUN_PH(8) RUN_PH(9)
;     RUN_PH(10) RUN_PH(11) RUN_PH(12) RUN_PH(13) RUN_PH(14) RUN_PH(15) RUN_PH(16) RUN_PH(17)
.LBB0_508:
	s_cmp_gt_i32 s94, 4
	s_waitcnt lgkmcnt(0)
	s_cselect_b64 s[0:1], -1, 0
	s_cmp_lt_i32 s95, 5
	s_cselect_b64 s[2:3], -1, 0
	s_or_b64 s[0:1], s[0:1], s[2:3]
	s_and_b64 vcc, exec, s[0:1]
	s_cbranch_vccnz .LBB0_585
	s_cmp_eq_u32 s94, 4
	s_cbranch_scc1 .LBB0_563
	s_waitcnt vmcnt(0)
	s_waitcnt vmcnt(0)
	v_cmp_lt_u32_e32 vcc, 63, v0
	s_and_saveexec_b64 s[0:1], vcc
	s_getpc_b64 s[2:3]
	v_lshlrev_b32_e32 v1, 6, v0
	global_load_dword v1, v1, s[2:3] offset:-4096
	s_mov_b64 exec, s[0:1]
	s_nop 0
	s_barrier
	s_and_saveexec_b64 s[4:5], s[92:93]
	s_cbranch_execz .LBB0_562
	v_mov_b32_e32 v1, 0
	s_waitcnt vmcnt(0) expcnt(0) lgkmcnt(0)
	ds_read_b32 v3, v1
	ds_read_b32 v2, v1 offset:4
	s_waitcnt lgkmcnt(1)
	v_cmp_ne_u32_e32 vcc, 0, v3
	s_cbranch_vccnz .LBB0_526
	s_add_u32 s6, s88, 0x2e9d8200
	s_addc_u32 s7, s89, 0
	s_add_u32 s8, s88, 0x2e9d8400
	s_addc_u32 s9, s89, 0
	s_add_u32 s12, s88, 0x2e9d8500
	s_addc_u32 s13, s89, 0
	s_add_u32 s14, s88, 0x2e9d8600
	s_addc_u32 s15, s89, 0
	s_add_u32 s16, s88, 0x2e9d8700
	s_addc_u32 s17, s89, 0
	s_add_u32 s18, s88, 0x2e9d8800
	s_addc_u32 s19, s89, 0
	s_add_u32 s20, s88, 0x2e9d8900
	s_addc_u32 s21, s89, 0
	s_add_u32 s22, s88, 0x2e9d8a00
	s_addc_u32 s23, s89, 0
	s_add_u32 s24, s88, 0x2e9d8b00
	s_addc_u32 s25, s89, 0
	s_add_u32 s26, s88, 0x2e9d8c00
	s_addc_u32 s27, s89, 0
	s_add_u32 s28, s88, 0x2e9d8d00
	s_addc_u32 s29, s89, 0
	s_add_u32 s34, s88, 0x2e9d8e00
	s_addc_u32 s35, s89, 0
	s_add_u32 s36, s88, 0x2e9d8f00
	s_addc_u32 s37, s89, 0
	s_add_u32 s38, s88, 0x2e9d9000
	s_addc_u32 s39, s89, 0
	s_load_dwordx2 s[0:1], s[86:87], 0xe0
	s_load_dword s2, s[86:87], 0xe8
	s_add_u32 s40, s88, 0x2e9d9100
	s_addc_u32 s41, s89, 0
	s_add_u32 s42, s88, 0x2e9d9200
	s_addc_u32 s43, s89, 0
	s_waitcnt lgkmcnt(0)
	s_mul_i32 s0, s1, s0
	s_add_u32 s44, s88, 0x2e9d9300
	s_mul_i32 s0, s0, s2
	s_addc_u32 s45, s89, 0
	s_mov_b32 s1, 1
	s_branch .LBB0_514

; #define RUN_PH(k) if (ph0 <= (k) && (k) < ph1) { if ((k) != ph0) xcd_barrier(xb); run_phase<(k)>(kp, shm); }
; __device__ __forceinline__ void xcd_barrier(const XcdBarrier& b) {
;     asm volatile("s_waitcnt vmcnt(0)" ::: "memory");
;     __syncthreads();
;     if (threadIdx.x == 0) {
;         unsigned* bar = b.bar;
;         __builtin_amdgcn_s_waitcnt(0);
;         unsigned nloc = b.st[0], nx = b.st[1];
;         if (nloc == 0u) { xcd_barrier_complete(bar, b.x, nloc, nx); b.st[0] = nloc; b.st[1] = nx; }
; __global__ void __launch_bounds__(512, 2) mega(Params P, int ph0, int ph1) {
;     ...
;     RUN_PH(0) RUN_PH(1) RUN_PH(2) RUN_PH(3) RUN_PH(4) RUN_PH(5) RUN_PH(6) RUN_PH(7) RUN_PH(8) RUN_PH(9)
;     RUN_PH(10) RUN_PH(11) RUN_PH(12) RUN_PH(13) RUN_PH(14) RUN_PH(15) RUN_PH(16) RUN_PH(17)
.LBB0_585:
	s_cmp_gt_i32 s94, 5
	s_cselect_b64 s[0:1], -1, 0
	s_cmp_lt_i32 s95, 6
	s_cselect_b64 s[2:3], -1, 0
	s_or_b64 s[0:1], s[0:1], s[2:3]
	s_and_b64 vcc, exec, s[0:1]
	s_cbranch_vccnz .LBB0_657
	s_cmp_eq_u32 s94, 5
	s_cbranch_scc1 .LBB0_640
	s_waitcnt vmcnt(0)
	s_waitcnt vmcnt(0)
	v_cmp_lt_u32_e32 vcc, 63, v0
	s_and_saveexec_b64 s[0:1], vcc
	s_getpc_b64 s[2:3]
	v_lshlrev_b32_e32 v1, 6, v0
	global_load_dword v1, v1, s[2:3] offset:-4096
	s_mov_b64 exec, s[0:1]
	s_nop 0
	s_barrier
	s_and_saveexec_b64 s[4:5], s[92:93]
	s_cbranch_execz .LBB0_639
	v_mov_b32_e32 v1, 0
	s_waitcnt vmcnt(0) expcnt(0) lgkmcnt(0)
	ds_read_b32 v3, v1
	ds_read_b32 v2, v1 offset:4
	s_waitcnt lgkmcnt(1)
	v_cmp_ne_u32_e32 vcc, 0, v3
	s_cbranch_vccnz .LBB0_603
	s_add_u32 s6, s88, 0x2e9d8200
	s_addc_u32 s7, s89, 0
	s_add_u32 s8, s88, 0x2e9d8400
	s_addc_u32 s9, s89, 0
	s_add_u32 s12, s88, 0x2e9d8500
	s_addc_u32 s13, s89, 0
	s_add_u32 s14, s88, 0x2e9d8600
	s_addc_u32 s15, s89, 0
	s_add_u32 s16, s88, 0x2e9d8700
	s_addc_u32 s17, s89, 0
	s_add_u32 s18, s88, 0x2e9d8800
	s_addc_u32 s19, s89, 0
	s_add_u32 s20, s88, 0x2e9d8900
	s_addc_u32 s21, s89, 0
	s_add_u32 s22, s88, 0x2e9d8a00
	s_addc_u32 s23, s89, 0
	s_add_u32 s24, s88, 0x2e9d8b00
	s_addc_u32 s25, s89, 0
	s_add_u32 s26, s88, 0x2e9d8c00
	s_addc_u32 s27, s89, 0
	s_add_u32 s28, s88, 0x2e9d8d00
	s_addc_u32 s29, s89, 0
	s_add_u32 s34, s88, 0x2e9d8e00
	s_addc_u32 s35, s89, 0
	s_add_u32 s36, s88, 0x2e9d8f00
	s_addc_u32 s37, s89, 0
	s_add_u32 s38, s88, 0x2e9d9000
	s_addc_u32 s39, s89, 0
	s_load_dwordx2 s[0:1], s[86:87], 0xe0
	s_load_dword s2, s[86:87], 0xe8
	s_add_u32 s40, s88, 0x2e9d9100
	s_addc_u32 s41, s89, 0
	s_add_u32 s42, s88, 0x2e9d9200
	s_addc_u32 s43, s89, 0
	s_waitcnt lgkmcnt(0)
	s_mul_i32 s0, s1, s0
	s_add_u32 s44, s88, 0x2e9d9300
	s_mul_i32 s0, s0, s2
	s_addc_u32 s45, s89, 0
	s_mov_b32 s1, 1
	s_branch .LBB0_591

; #define RUN_PH(k) if (ph0 <= (k) && (k) < ph1) { if ((k) != ph0) xcd_barrier(xb); run_phase<(k)>(kp, shm); }
; __device__ __forceinline__ void xcd_barrier(const XcdBarrier& b) {
;     asm volatile("s_waitcnt vmcnt(0)" ::: "memory");
;     __syncthreads();
;     if (threadIdx.x == 0) {
;         unsigned* bar = b.bar;
;         __builtin_amdgcn_s_waitcnt(0);
;         unsigned nloc = b.st[0], nx = b.st[1];
;         if (nloc == 0u) { xcd_barrier_complete(bar, b.x, nloc, nx); b.st[0] = nloc; b.st[1] = nx; }
; __global__ void __launch_bounds__(512, 2) mega(Params P, int ph0, int ph1) {
;     ...
;     RUN_PH(0) RUN_PH(1) RUN_PH(2) RUN_PH(3) RUN_PH(4) RUN_PH(5) RUN_PH(6) RUN_PH(7) RUN_PH(8) RUN_PH(9)
;     RUN_PH(10) RUN_PH(11) RUN_PH(12) RUN_PH(13) RUN_PH(14) RUN_PH(15) RUN_PH(16) RUN_PH(17)
.LBB0_657:
	s_cmp_gt_i32 s94, 6
	s_waitcnt lgkmcnt(0)
	s_cselect_b64 s[0:1], -1, 0
	s_cmp_lt_i32 s95, 7
	s_cselect_b64 s[2:3], -1, 0
	s_or_b64 s[0:1], s[0:1], s[2:3]
	s_and_b64 vcc, exec, s[0:1]
	s_cbranch_vccnz .LBB0_766
	s_cmp_eq_u32 s94, 6
	s_cbranch_scc1 .LBB0_712
	s_waitcnt vmcnt(0)
	s_waitcnt vmcnt(0)
	v_cmp_lt_u32_e32 vcc, 63, v0
	s_and_saveexec_b64 s[0:1], vcc
	s_getpc_b64 s[2:3]
	v_lshlrev_b32_e32 v1, 6, v0
	global_load_dword v1, v1, s[2:3] offset:-4096
	s_mov_b64 exec, s[0:1]
	s_nop 0
	s_barrier
	s_and_saveexec_b64 s[4:5], s[92:93]
	s_cbranch_execz .LBB0_711
	v_mov_b32_e32 v1, 0
	s_waitcnt vmcnt(0) expcnt(0) lgkmcnt(0)
	ds_read_b32 v3, v1
	ds_read_b32 v2, v1 offset:4
	s_waitcnt lgkmcnt(1)
	v_cmp_ne_u32_e32 vcc, 0, v3
	s_cbranch_vccnz .LBB0_675
	s_add_u32 s6, s88, 0x2e9d8200
	s_addc_u32 s7, s89, 0
	s_add_u32 s8, s88, 0x2e9d8400
	s_addc_u32 s9, s89, 0
	s_add_u32 s12, s88, 0x2e9d8500
	s_addc_u32 s13, s89, 0
	s_add_u32 s14, s88, 0x2e9d8600
	s_addc_u32 s15, s89, 0
	s_add_u32 s16, s88, 0x2e9d8700
	s_addc_u32 s17, s89, 0
	s_add_u32 s18, s88, 0x2e9d8800
	s_addc_u32 s19, s89, 0
	s_add_u32 s20, s88, 0x2e9d8900
	s_addc_u32 s21, s89, 0
	s_add_u32 s22, s88, 0x2e9d8a00
	s_addc_u32 s23, s89, 0
	s_add_u32 s24, s88, 0x2e9d8b00
	s_addc_u32 s25, s89, 0
	s_add_u32 s26, s88, 0x2e9d8c00
	s_addc_u32 s27, s89, 0
	s_add_u32 s28, s88, 0x2e9d8d00
	s_addc_u32 s29, s89, 0
	s_add_u32 s34, s88, 0x2e9d8e00
	s_addc_u32 s35, s89, 0
	s_add_u32 s36, s88, 0x2e9d8f00
	s_addc_u32 s37, s89, 0
	s_add_u32 s38, s88, 0x2e9d9000
	s_addc_u32 s39, s89, 0
	s_load_dwordx2 s[0:1], s[86:87], 0xe0
	s_load_dword s2, s[86:87], 0xe8
	s_add_u32 s40, s88, 0x2e9d9100
	s_addc_u32 s41, s89, 0
	s_add_u32 s42, s88, 0x2e9d9200
	s_addc_u32 s43, s89, 0
	s_waitcnt lgkmcnt(0)
	s_mul_i32 s0, s1, s0
	s_add_u32 s44, s88, 0x2e9d9300
	s_mul_i32 s0, s0, s2
	s_addc_u32 s45, s89, 0
	s_mov_b32 s1, 1
	s_branch .LBB0_663

; #define RUN_PH(k) if (ph0 <= (k) && (k) < ph1) { if ((k) != ph0) xcd_barrier(xb); run_phase<(k)>(kp, shm); }
; __device__ __forceinline__ void xcd_barrier(const XcdBarrier& b) {
;     asm volatile("s_waitcnt vmcnt(0)" ::: "memory");
;     __syncthreads();
;     if (threadIdx.x == 0) {
;         unsigned* bar = b.bar;
;         __builtin_amdgcn_s_waitcnt(0);
;         unsigned nloc = b.st[0], nx = b.st[1];
;         if (nloc == 0u) { xcd_barrier_complete(bar, b.x, nloc, nx); b.st[0] = nloc; b.st[1] = nx; }
; __global__ void __launch_bounds__(512, 2) mega(Params P, int ph0, int ph1) {
;     ...
;     RUN_PH(0) RUN_PH(1) RUN_PH(2) RUN_PH(3) RUN_PH(4) RUN_PH(5) RUN_PH(6) RUN_PH(7) RUN_PH(8) RUN_PH(9)
;     RUN_PH(10) RUN_PH(11) RUN_PH(12) RUN_PH(13) RUN_PH(14) RUN_PH(15) RUN_PH(16) RUN_PH(17)
.LBB0_766:
	s_cmp_gt_i32 s94, 7
	s_cselect_b64 s[0:1], -1, 0
	s_cmp_lt_i32 s95, 8
	s_cselect_b64 s[2:3], -1, 0
	s_or_b64 s[0:1], s[0:1], s[2:3]
	s_and_b64 vcc, exec, s[0:1]
	s_cbranch_vccnz .LBB0_879
	s_cmp_eq_u32 s94, 7
	s_cbranch_scc1 .LBB0_821
	s_waitcnt vmcnt(0)
	s_waitcnt vmcnt(0) lgkmcnt(0)
	v_cmp_lt_u32_e32 vcc, 63, v0
	s_and_saveexec_b64 s[0:1], vcc
	s_getpc_b64 s[2:3]
	v_lshlrev_b32_e32 v1, 6, v0
	global_load_dword v1, v1, s[2:3] offset:-4096
	s_mov_b64 exec, s[0:1]
	s_nop 0
	s_barrier
	s_and_saveexec_b64 s[4:5], s[92:93]
	s_cbranch_execz .LBB0_820
	v_mov_b32_e32 v1, 0
	s_waitcnt vmcnt(0) expcnt(0) lgkmcnt(0)
	ds_read_b32 v3, v1
	ds_read_b32 v2, v1 offset:4
	s_waitcnt lgkmcnt(1)
	v_cmp_ne_u32_e32 vcc, 0, v3
	s_cbranch_vccnz .LBB0_784
	s_add_u32 s6, s88, 0x2e9d8200
	s_addc_u32 s7, s89, 0
	s_add_u32 s8, s88, 0x2e9d8400
	s_addc_u32 s9, s89, 0
	s_add_u32 s12, s88, 0x2e9d8500
	s_addc_u32 s13, s89, 0
	s_add_u32 s14, s88, 0x2e9d8600
	s_addc_u32 s15, s89, 0
	s_add_u32 s16, s88, 0x2e9d8700
	s_addc_u32 s17, s89, 0
	s_add_u32 s18, s88, 0x2e9d8800
	s_addc_u32 s19, s89, 0
	s_add_u32 s20, s88, 0x2e9d8900
	s_addc_u32 s21, s89, 0
	s_add_u32 s22, s88, 0x2e9d8a00
	s_addc_u32 s23, s89, 0
	s_add_u32 s24, s88, 0x2e9d8b00
	s_addc_u32 s25, s89, 0
	s_add_u32 s26, s88, 0x2e9d8c00
	s_addc_u32 s27, s89, 0
	s_add_u32 s28, s88, 0x2e9d8d00
	s_addc_u32 s29, s89, 0
	s_add_u32 s34, s88, 0x2e9d8e00
	s_addc_u32 s35, s89, 0
	s_add_u32 s36, s88, 0x2e9d8f00
	s_addc_u32 s37, s89, 0
	s_add_u32 s38, s88, 0x2e9d9000
	s_addc_u32 s39, s89, 0
	s_load_dwordx2 s[0:1], s[86:87], 0xe0
	s_load_dword s2, s[86:87], 0xe8
	s_add_u32 s40, s88, 0x2e9d9100
	s_addc_u32 s41, s89, 0
	s_add_u32 s42, s88, 0x2e9d9200
	s_addc_u32 s43, s89, 0
	s_waitcnt lgkmcnt(0)
	s_mul_i32 s0, s1, s0
	s_add_u32 s44, s88, 0x2e9d9300
	s_mul_i32 s0, s0, s2
	s_addc_u32 s45, s89, 0
	s_mov_b32 s1, 1
	s_branch .LBB0_772

; #define RUN_PH(k) if (ph0 <= (k) && (k) < ph1) { if ((k) != ph0) xcd_barrier(xb); run_phase<(k)>(kp, shm); }
; __device__ __forceinline__ void xcd_barrier(const XcdBarrier& b) {
;     asm volatile("s_waitcnt vmcnt(0)" ::: "memory");
;     __syncthreads();
;     if (threadIdx.x == 0) {
;         unsigned* bar = b.bar;
;         __builtin_amdgcn_s_waitcnt(0);
;         unsigned nloc = b.st[0], nx = b.st[1];
;         if (nloc == 0u) { xcd_barrier_complete(bar, b.x, nloc, nx); b.st[0] = nloc; b.st[1] = nx; }
; __global__ void __launch_bounds__(512, 2) mega(Params P, int ph0, int ph1) {
;     ...
;     RUN_PH(0) RUN_PH(1) RUN_PH(2) RUN_PH(3) RUN_PH(4) RUN_PH(5) RUN_PH(6) RUN_PH(7) RUN_PH(8) RUN_PH(9)
;     RUN_PH(10) RUN_PH(11) RUN_PH(12) RUN_PH(13) RUN_PH(14) RUN_PH(15) RUN_PH(16) RUN_PH(17)
.LBB0_879:
	s_cmp_gt_i32 s94, 8
	s_cselect_b64 s[0:1], -1, 0
	s_cmp_lt_i32 s95, 9
	s_cselect_b64 s[2:3], -1, 0
	s_or_b64 s[0:1], s[0:1], s[2:3]
	s_and_b64 vcc, exec, s[0:1]
	s_cbranch_vccnz .LBB0_962
	s_cmp_eq_u32 s94, 8
	s_cbranch_scc1 .LBB0_934
	s_waitcnt vmcnt(0)
	s_waitcnt vmcnt(0) lgkmcnt(0)
	v_cmp_lt_u32_e32 vcc, 63, v0
	s_and_saveexec_b64 s[0:1], vcc
	s_getpc_b64 s[2:3]
	v_lshlrev_b32_e32 v1, 6, v0
	global_load_dword v1, v1, s[2:3] offset:-4096
	s_mov_b64 exec, s[0:1]
	s_nop 0
	s_barrier
	s_and_saveexec_b64 s[4:5], s[92:93]
	s_cbranch_execz .LBB0_933
	v_mov_b32_e32 v1, 0
	s_waitcnt vmcnt(0) expcnt(0) lgkmcnt(0)
	ds_read_b32 v3, v1
	ds_read_b32 v2, v1 offset:4
	s_waitcnt lgkmcnt(1)
	v_cmp_ne_u32_e32 vcc, 0, v3
	s_cbranch_vccnz .LBB0_897
	s_add_u32 s6, s88, 0x2e9d8200
	s_addc_u32 s7, s89, 0
	s_add_u32 s8, s88, 0x2e9d8400
	s_addc_u32 s9, s89, 0
	s_add_u32 s12, s88, 0x2e9d8500
	s_addc_u32 s13, s89, 0
	s_add_u32 s14, s88, 0x2e9d8600
	s_addc_u32 s15, s89, 0
	s_add_u32 s16, s88, 0x2e9d8700
	s_addc_u32 s17, s89, 0
	s_add_u32 s18, s88, 0x2e9d8800
	s_addc_u32 s19, s89, 0
	s_add_u32 s20, s88, 0x2e9d8900
	s_addc_u32 s21, s89, 0
	s_add_u32 s22, s88, 0x2e9d8a00
	s_addc_u32 s23, s89, 0
	s_add_u32 s24, s88, 0x2e9d8b00
	s_addc_u32 s25, s89, 0
	s_add_u32 s26, s88, 0x2e9d8c00
	s_addc_u32 s27, s89, 0
	s_add_u32 s28, s88, 0x2e9d8d00
	s_addc_u32 s29, s89, 0
	s_add_u32 s34, s88, 0x2e9d8e00
	s_addc_u32 s35, s89, 0
	s_add_u32 s36, s88, 0x2e9d8f00
	s_addc_u32 s37, s89, 0
	s_add_u32 s38, s88, 0x2e9d9000
	s_addc_u32 s39, s89, 0
	s_load_dwordx2 s[0:1], s[86:87], 0xe0
	s_load_dword s2, s[86:87], 0xe8
	s_add_u32 s40, s88, 0x2e9d9100
	s_addc_u32 s41, s89, 0
	s_add_u32 s42, s88, 0x2e9d9200
	s_addc_u32 s43, s89, 0
	s_waitcnt lgkmcnt(0)
	s_mul_i32 s0, s1, s0
	s_add_u32 s44, s88, 0x2e9d9300
	s_mul_i32 s0, s0, s2
	s_addc_u32 s45, s89, 0
	s_mov_b32 s1, 1
	s_branch .LBB0_885

; #define RUN_PH(k) if (ph0 <= (k) && (k) < ph1) { if ((k) != ph0) xcd_barrier(xb); run_phase<(k)>(kp, shm); }
; __device__ __forceinline__ void xcd_barrier(const XcdBarrier& b) {
;     asm volatile("s_waitcnt vmcnt(0)" ::: "memory");
;     __syncthreads();
;     if (threadIdx.x == 0) {
;         unsigned* bar = b.bar;
;         __builtin_amdgcn_s_waitcnt(0);
;         unsigned nloc = b.st[0], nx = b.st[1];
;         if (nloc == 0u) { xcd_barrier_complete(bar, b.x, nloc, nx); b.st[0] = nloc; b.st[1] = nx; }
; __global__ void __launch_bounds__(512, 2) mega(Params P, int ph0, int ph1) {
;     ...
;     RUN_PH(0) RUN_PH(1) RUN_PH(2) RUN_PH(3) RUN_PH(4) RUN_PH(5) RUN_PH(6) RUN_PH(7) RUN_PH(8) RUN_PH(9)
;     RUN_PH(10) RUN_PH(11) RUN_PH(12) RUN_PH(13) RUN_PH(14) RUN_PH(15) RUN_PH(16) RUN_PH(17)
.LBB0_962:
	s_cmp_gt_i32 s94, 9
	s_waitcnt lgkmcnt(0)
	s_cselect_b64 s[0:1], -1, 0
	s_cmp_lt_i32 s95, 10
	s_cselect_b64 s[2:3], -1, 0
	s_or_b64 s[0:1], s[0:1], s[2:3]
	s_and_b64 vcc, exec, s[0:1]
	s_cbranch_vccnz .LBB0_1023
	s_cmp_eq_u32 s94, 9
	s_cbranch_scc1 .LBB0_1017
	s_waitcnt vmcnt(0)
	s_waitcnt vmcnt(0)
	v_cmp_lt_u32_e32 vcc, 63, v0
	s_and_saveexec_b64 s[0:1], vcc
	s_getpc_b64 s[2:3]
	v_lshlrev_b32_e32 v1, 6, v0
	global_load_dword v1, v1, s[2:3] offset:-4096
	s_mov_b64 exec, s[0:1]
	s_nop 0
	s_barrier
	s_and_saveexec_b64 s[4:5], s[92:93]
	s_cbranch_execz .LBB0_1016
	v_mov_b32_e32 v1, 0
	s_waitcnt vmcnt(0) expcnt(0) lgkmcnt(0)
	ds_read_b32 v3, v1
	ds_read_b32 v2, v1 offset:4
	s_waitcnt lgkmcnt(1)
	v_cmp_ne_u32_e32 vcc, 0, v3
	s_cbranch_vccnz .LBB0_980
	s_add_u32 s6, s88, 0x2e9d8200
	s_addc_u32 s7, s89, 0
	s_add_u32 s8, s88, 0x2e9d8400
	s_addc_u32 s9, s89, 0
	s_add_u32 s12, s88, 0x2e9d8500
	s_addc_u32 s13, s89, 0
	s_add_u32 s14, s88, 0x2e9d8600
	s_addc_u32 s15, s89, 0
	s_add_u32 s16, s88, 0x2e9d8700
	s_addc_u32 s17, s89, 0
	s_add_u32 s18, s88, 0x2e9d8800
	s_addc_u32 s19, s89, 0
	s_add_u32 s20, s88, 0x2e9d8900
	s_addc_u32 s21, s89, 0
	s_add_u32 s22, s88, 0x2e9d8a00
	s_addc_u32 s23, s89, 0
	s_add_u32 s24, s88, 0x2e9d8b00
	s_addc_u32 s25, s89, 0
	s_add_u32 s26, s88, 0x2e9d8c00
	s_addc_u32 s27, s89, 0
	s_add_u32 s28, s88, 0x2e9d8d00
	s_addc_u32 s29, s89, 0
	s_add_u32 s34, s88, 0x2e9d8e00
	s_addc_u32 s35, s89, 0
	s_add_u32 s36, s88, 0x2e9d8f00
	s_addc_u32 s37, s89, 0
	s_add_u32 s38, s88, 0x2e9d9000
	s_addc_u32 s39, s89, 0
	s_load_dwordx2 s[0:1], s[86:87], 0xe0
	s_load_dword s2, s[86:87], 0xe8
	s_add_u32 s40, s88, 0x2e9d9100
	s_addc_u32 s41, s89, 0
	s_add_u32 s42, s88, 0x2e9d9200
	s_addc_u32 s43, s89, 0
	s_waitcnt lgkmcnt(0)
	s_mul_i32 s0, s1, s0
	s_add_u32 s44, s88, 0x2e9d9300
	s_mul_i32 s0, s0, s2
	s_addc_u32 s45, s89, 0
	s_mov_b32 s1, 1
	s_branch .LBB0_968

; #define RUN_PH(k) if (ph0 <= (k) && (k) < ph1) { if ((k) != ph0) xcd_barrier(xb); run_phase<(k)>(kp, shm); }
; __device__ __forceinline__ void xcd_barrier(const XcdBarrier& b) {
;     asm volatile("s_waitcnt vmcnt(0)" ::: "memory");
;     __syncthreads();
;     if (threadIdx.x == 0) {
;         unsigned* bar = b.bar;
;         __builtin_amdgcn_s_waitcnt(0);
;         unsigned nloc = b.st[0], nx = b.st[1];
;         if (nloc == 0u) { xcd_barrier_complete(bar, b.x, nloc, nx); b.st[0] = nloc; b.st[1] = nx; }
; __global__ void __launch_bounds__(512, 2) mega(Params P, int ph0, int ph1) {
;     ...
;     RUN_PH(0) RUN_PH(1) RUN_PH(2) RUN_PH(3) RUN_PH(4) RUN_PH(5) RUN_PH(6) RUN_PH(7) RUN_PH(8) RUN_PH(9)
;     RUN_PH(10) RUN_PH(11) RUN_PH(12) RUN_PH(13) RUN_PH(14) RUN_PH(15) RUN_PH(16) RUN_PH(17)
.LBB0_1023:
	s_cmp_gt_i32 s94, 10
	s_cselect_b64 s[0:1], -1, 0
	s_cmp_lt_i32 s95, 11
	s_cselect_b64 s[2:3], -1, 0
	s_or_b64 s[0:1], s[0:1], s[2:3]
	s_and_b64 vcc, exec, s[0:1]
	s_cbranch_vccnz .LBB0_1114
	s_cmp_eq_u32 s94, 10
	s_cbranch_scc1 .LBB0_1078
	s_waitcnt vmcnt(0)
	s_waitcnt vmcnt(0)
	v_cmp_lt_u32_e32 vcc, 63, v0
	s_and_saveexec_b64 s[0:1], vcc
	s_getpc_b64 s[2:3]
	v_lshlrev_b32_e32 v1, 6, v0
	global_load_dword v1, v1, s[2:3] offset:-4096
	s_mov_b64 exec, s[0:1]
	s_nop 0
	s_barrier
	s_and_saveexec_b64 s[4:5], s[92:93]
	s_cbranch_execz .LBB0_1077
	v_mov_b32_e32 v1, 0
	s_waitcnt vmcnt(0) expcnt(0) lgkmcnt(0)
	ds_read_b32 v3, v1
	ds_read_b32 v2, v1 offset:4
	s_waitcnt lgkmcnt(1)
	v_cmp_ne_u32_e32 vcc, 0, v3
	s_cbranch_vccnz .LBB0_1041
	s_add_u32 s6, s88, 0x2e9d8200
	s_addc_u32 s7, s89, 0
	s_add_u32 s8, s88, 0x2e9d8400
	s_addc_u32 s9, s89, 0
	s_add_u32 s12, s88, 0x2e9d8500
	s_addc_u32 s13, s89, 0
	s_add_u32 s14, s88, 0x2e9d8600
	s_addc_u32 s15, s89, 0
	s_add_u32 s16, s88, 0x2e9d8700
	s_addc_u32 s17, s89, 0
	s_add_u32 s18, s88, 0x2e9d8800
	s_addc_u32 s19, s89, 0
	s_add_u32 s20, s88, 0x2e9d8900
	s_addc_u32 s21, s89, 0
	s_add_u32 s22, s88, 0x2e9d8a00
	s_addc_u32 s23, s89, 0
	s_add_u32 s24, s88, 0x2e9d8b00
	s_addc_u32 s25, s89, 0
	s_add_u32 s26, s88, 0x2e9d8c00
	s_addc_u32 s27, s89, 0
	s_add_u32 s28, s88, 0x2e9d8d00
	s_addc_u32 s29, s89, 0
	s_add_u32 s34, s88, 0x2e9d8e00
	s_addc_u32 s35, s89, 0
	s_add_u32 s36, s88, 0x2e9d8f00
	s_addc_u32 s37, s89, 0
	s_add_u32 s38, s88, 0x2e9d9000
	s_addc_u32 s39, s89, 0
	s_load_dwordx2 s[0:1], s[86:87], 0xe0
	s_load_dword s2, s[86:87], 0xe8
	s_add_u32 s40, s88, 0x2e9d9100
	s_addc_u32 s41, s89, 0
	s_add_u32 s42, s88, 0x2e9d9200
	s_addc_u32 s43, s89, 0
	s_waitcnt lgkmcnt(0)
	s_mul_i32 s0, s1, s0
	s_add_u32 s44, s88, 0x2e9d9300
	s_mul_i32 s0, s0, s2
	s_addc_u32 s45, s89, 0
	s_mov_b32 s1, 1
	s_branch .LBB0_1029

; #define RUN_PH(k) if (ph0 <= (k) && (k) < ph1) { if ((k) != ph0) xcd_barrier(xb); run_phase<(k)>(kp, shm); }
; __device__ __forceinline__ void xcd_barrier(const XcdBarrier& b) {
;     asm volatile("s_waitcnt vmcnt(0)" ::: "memory");
;     __syncthreads();
;     if (threadIdx.x == 0) {
;         unsigned* bar = b.bar;
;         __builtin_amdgcn_s_waitcnt(0);
;         unsigned nloc = b.st[0], nx = b.st[1];
;         if (nloc == 0u) { xcd_barrier_complete(bar, b.x, nloc, nx); b.st[0] = nloc; b.st[1] = nx; }
; __global__ void __launch_bounds__(512, 2) mega(Params P, int ph0, int ph1) {
;     ...
;     RUN_PH(0) RUN_PH(1) RUN_PH(2) RUN_PH(3) RUN_PH(4) RUN_PH(5) RUN_PH(6) RUN_PH(7) RUN_PH(8) RUN_PH(9)
;     RUN_PH(10) RUN_PH(11) RUN_PH(12) RUN_PH(13) RUN_PH(14) RUN_PH(15) RUN_PH(16) RUN_PH(17)
.LBB0_1114:
	s_cmp_gt_i32 s94, 11
	s_waitcnt lgkmcnt(0)
	s_cselect_b64 s[0:1], -1, 0
	s_cmp_lt_i32 s95, 12
	s_cselect_b64 s[2:3], -1, 0
	s_or_b64 s[0:1], s[0:1], s[2:3]
	s_and_b64 vcc, exec, s[0:1]
	s_cbranch_vccnz .LBB0_1186
	s_cmp_eq_u32 s94, 11
	s_cbranch_scc1 .LBB0_1169
	s_waitcnt vmcnt(0)
	s_waitcnt vmcnt(0)
	v_cmp_lt_u32_e32 vcc, 63, v0
	s_and_saveexec_b64 s[0:1], vcc
	s_getpc_b64 s[2:3]
	v_lshlrev_b32_e32 v1, 6, v0
	global_load_dword v1, v1, s[2:3] offset:-4096
	s_mov_b64 exec, s[0:1]
	s_nop 0
	s_barrier
	s_and_saveexec_b64 s[4:5], s[92:93]
	s_cbranch_execz .LBB0_1168
	v_mov_b32_e32 v1, 0
	s_waitcnt vmcnt(0) expcnt(0) lgkmcnt(0)
	ds_read_b32 v3, v1
	ds_read_b32 v2, v1 offset:4
	s_waitcnt lgkmcnt(1)
	v_cmp_ne_u32_e32 vcc, 0, v3
	s_cbranch_vccnz .LBB0_1132
	s_add_u32 s6, s88, 0x2e9d8200
	s_addc_u32 s7, s89, 0
	s_add_u32 s8, s88, 0x2e9d8400
	s_addc_u32 s9, s89, 0
	s_add_u32 s12, s88, 0x2e9d8500
	s_addc_u32 s13, s89, 0
	s_add_u32 s14, s88, 0x2e9d8600
	s_addc_u32 s15, s89, 0
	s_add_u32 s16, s88, 0x2e9d8700
	s_addc_u32 s17, s89, 0
	s_add_u32 s18, s88, 0x2e9d8800
	s_addc_u32 s19, s89, 0
	s_add_u32 s20, s88, 0x2e9d8900
	s_addc_u32 s21, s89, 0
	s_add_u32 s22, s88, 0x2e9d8a00
	s_addc_u32 s23, s89, 0
	s_add_u32 s24, s88, 0x2e9d8b00
	s_addc_u32 s25, s89, 0
	s_add_u32 s26, s88, 0x2e9d8c00
	s_addc_u32 s27, s89, 0
	s_add_u32 s28, s88, 0x2e9d8d00
	s_addc_u32 s29, s89, 0
	s_add_u32 s34, s88, 0x2e9d8e00
	s_addc_u32 s35, s89, 0
	s_add_u32 s36, s88, 0x2e9d8f00
	s_addc_u32 s37, s89, 0
	s_add_u32 s38, s88, 0x2e9d9000
	s_addc_u32 s39, s89, 0
	s_load_dwordx2 s[0:1], s[86:87], 0xe0
	s_load_dword s2, s[86:87], 0xe8
	s_add_u32 s40, s88, 0x2e9d9100
	s_addc_u32 s41, s89, 0
	s_add_u32 s42, s88, 0x2e9d9200
	s_addc_u32 s43, s89, 0
	s_waitcnt lgkmcnt(0)
	s_mul_i32 s0, s1, s0
	s_add_u32 s44, s88, 0x2e9d9300
	s_mul_i32 s0, s0, s2
	s_addc_u32 s45, s89, 0
	s_mov_b32 s1, 1
	s_branch .LBB0_1120

; #define RUN_PH(k) if (ph0 <= (k) && (k) < ph1) { if ((k) != ph0) xcd_barrier(xb); run_phase<(k)>(kp, shm); }
; __device__ __forceinline__ void xcd_barrier(const XcdBarrier& b) {
;     asm volatile("s_waitcnt vmcnt(0)" ::: "memory");
;     __syncthreads();
;     if (threadIdx.x == 0) {
;         unsigned* bar = b.bar;
;         __builtin_amdgcn_s_waitcnt(0);
;         unsigned nloc = b.st[0], nx = b.st[1];
;         if (nloc == 0u) { xcd_barrier_complete(bar, b.x, nloc, nx); b.st[0] = nloc; b.st[1] = nx; }
; __global__ void __launch_bounds__(512, 2) mega(Params P, int ph0, int ph1) {
;     ...
;     RUN_PH(0) RUN_PH(1) RUN_PH(2) RUN_PH(3) RUN_PH(4) RUN_PH(5) RUN_PH(6) RUN_PH(7) RUN_PH(8) RUN_PH(9)
;     RUN_PH(10) RUN_PH(11) RUN_PH(12) RUN_PH(13) RUN_PH(14) RUN_PH(15) RUN_PH(16) RUN_PH(17)
.LBB0_1186:
	s_cmp_gt_i32 s94, 12
	s_waitcnt lgkmcnt(0)
	s_cselect_b64 s[0:1], -1, 0
	s_cmp_lt_i32 s95, 13
	s_cselect_b64 s[2:3], -1, 0
	s_or_b64 s[0:1], s[0:1], s[2:3]
	s_and_b64 vcc, exec, s[0:1]
	s_cbranch_vccnz .LBB0_1255
	s_cmp_eq_u32 s94, 12
	s_cbranch_scc1 .LBB0_1241
	s_waitcnt vmcnt(0)
	s_waitcnt vmcnt(0)
	v_cmp_lt_u32_e32 vcc, 63, v0
	s_and_saveexec_b64 s[0:1], vcc
	s_getpc_b64 s[2:3]
	v_lshlrev_b32_e32 v1, 6, v0
	global_load_dword v1, v1, s[2:3] offset:-4096
	s_mov_b64 exec, s[0:1]
	s_nop 0
	s_barrier
	s_and_saveexec_b64 s[4:5], s[92:93]
	s_cbranch_execz .LBB0_1240
	v_mov_b32_e32 v1, 0
	s_waitcnt vmcnt(0) expcnt(0) lgkmcnt(0)
	ds_read_b32 v3, v1
	ds_read_b32 v2, v1 offset:4
	s_waitcnt lgkmcnt(1)
	v_cmp_ne_u32_e32 vcc, 0, v3
	s_cbranch_vccnz .LBB0_1204
	s_add_u32 s6, s88, 0x2e9d8200
	s_addc_u32 s7, s89, 0
	s_add_u32 s8, s88, 0x2e9d8400
	s_addc_u32 s9, s89, 0
	s_add_u32 s12, s88, 0x2e9d8500
	s_addc_u32 s13, s89, 0
	s_add_u32 s14, s88, 0x2e9d8600
	s_addc_u32 s15, s89, 0
	s_add_u32 s16, s88, 0x2e9d8700
	s_addc_u32 s17, s89, 0
	s_add_u32 s18, s88, 0x2e9d8800
	s_addc_u32 s19, s89, 0
	s_add_u32 s20, s88, 0x2e9d8900
	s_addc_u32 s21, s89, 0
	s_add_u32 s22, s88, 0x2e9d8a00
	s_addc_u32 s23, s89, 0
	s_add_u32 s24, s88, 0x2e9d8b00
	s_addc_u32 s25, s89, 0
	s_add_u32 s26, s88, 0x2e9d8c00
	s_addc_u32 s27, s89, 0
	s_add_u32 s28, s88, 0x2e9d8d00
	s_addc_u32 s29, s89, 0
	s_add_u32 s34, s88, 0x2e9d8e00
	s_addc_u32 s35, s89, 0
	s_add_u32 s36, s88, 0x2e9d8f00
	s_addc_u32 s37, s89, 0
	s_add_u32 s38, s88, 0x2e9d9000
	s_addc_u32 s39, s89, 0
	s_load_dwordx2 s[0:1], s[86:87], 0xe0
	s_load_dword s2, s[86:87], 0xe8
	s_add_u32 s40, s88, 0x2e9d9100
	s_addc_u32 s41, s89, 0
	s_add_u32 s42, s88, 0x2e9d9200
	s_addc_u32 s43, s89, 0
	s_waitcnt lgkmcnt(0)
	s_mul_i32 s0, s1, s0
	s_add_u32 s44, s88, 0x2e9d9300
	s_mul_i32 s0, s0, s2
	s_addc_u32 s45, s89, 0
	s_mov_b32 s1, 1
	s_branch .LBB0_1192

; #define RUN_PH(k) if (ph0 <= (k) && (k) < ph1) { if ((k) != ph0) xcd_barrier(xb); run_phase<(k)>(kp, shm); }
; __device__ __forceinline__ void xcd_barrier(const XcdBarrier& b) {
;     asm volatile("s_waitcnt vmcnt(0)" ::: "memory");
;     __syncthreads();
;     if (threadIdx.x == 0) {
;         unsigned* bar = b.bar;
;         __builtin_amdgcn_s_waitcnt(0);
;         unsigned nloc = b.st[0], nx = b.st[1];
;         if (nloc == 0u) { xcd_barrier_complete(bar, b.x, nloc, nx); b.st[0] = nloc; b.st[1] = nx; }
; __global__ void __launch_bounds__(512, 2) mega(Params P, int ph0, int ph1) {
;     ...
;     RUN_PH(0) RUN_PH(1) RUN_PH(2) RUN_PH(3) RUN_PH(4) RUN_PH(5) RUN_PH(6) RUN_PH(7) RUN_PH(8) RUN_PH(9)
;     RUN_PH(10) RUN_PH(11) RUN_PH(12) RUN_PH(13) RUN_PH(14) RUN_PH(15) RUN_PH(16) RUN_PH(17)
.LBB0_1255:
	s_cmp_gt_i32 s94, 13
	s_waitcnt lgkmcnt(0)
	s_cselect_b64 s[0:1], -1, 0
	s_cmp_lt_i32 s95, 14
	s_cselect_b64 s[2:3], -1, 0
	s_or_b64 s[0:1], s[0:1], s[2:3]
	s_and_b64 vcc, exec, s[0:1]
	s_cbranch_vccnz .LBB0_1327
	s_cmp_eq_u32 s94, 13
	s_cbranch_scc1 .LBB0_1310
	s_waitcnt vmcnt(0)
	s_waitcnt vmcnt(0)
	v_cmp_lt_u32_e32 vcc, 63, v0
	s_and_saveexec_b64 s[0:1], vcc
	s_getpc_b64 s[2:3]
	v_lshlrev_b32_e32 v1, 6, v0
	global_load_dword v1, v1, s[2:3] offset:-4096
	s_mov_b64 exec, s[0:1]
	s_nop 0
	s_barrier
	s_and_saveexec_b64 s[4:5], s[92:93]
	s_cbranch_execz .LBB0_1309
	v_mov_b32_e32 v1, 0
	s_waitcnt vmcnt(0) expcnt(0) lgkmcnt(0)
	ds_read_b32 v3, v1
	ds_read_b32 v2, v1 offset:4
	s_waitcnt lgkmcnt(1)
	v_cmp_ne_u32_e32 vcc, 0, v3
	s_cbranch_vccnz .LBB0_1273
	s_add_u32 s6, s88, 0x2e9d8200
	s_addc_u32 s7, s89, 0
	s_add_u32 s8, s88, 0x2e9d8400
	s_addc_u32 s9, s89, 0
	s_add_u32 s12, s88, 0x2e9d8500
	s_addc_u32 s13, s89, 0
	s_add_u32 s14, s88, 0x2e9d8600
	s_addc_u32 s15, s89, 0
	s_add_u32 s16, s88, 0x2e9d8700
	s_addc_u32 s17, s89, 0
	s_add_u32 s18, s88, 0x2e9d8800
	s_addc_u32 s19, s89, 0
	s_add_u32 s20, s88, 0x2e9d8900
	s_addc_u32 s21, s89, 0
	s_add_u32 s22, s88, 0x2e9d8a00
	s_addc_u32 s23, s89, 0
	s_add_u32 s24, s88, 0x2e9d8b00
	s_addc_u32 s25, s89, 0
	s_add_u32 s26, s88, 0x2e9d8c00
	s_addc_u32 s27, s89, 0
	s_add_u32 s28, s88, 0x2e9d8d00
	s_addc_u32 s29, s89, 0
	s_add_u32 s34, s88, 0x2e9d8e00
	s_addc_u32 s35, s89, 0
	s_add_u32 s36, s88, 0x2e9d8f00
	s_addc_u32 s37, s89, 0
	s_add_u32 s38, s88, 0x2e9d9000
	s_addc_u32 s39, s89, 0
	s_load_dwordx2 s[0:1], s[86:87], 0xe0
	s_load_dword s2, s[86:87], 0xe8
	s_add_u32 s40, s88, 0x2e9d9100
	s_addc_u32 s41, s89, 0
	s_add_u32 s42, s88, 0x2e9d9200
	s_addc_u32 s43, s89, 0
	s_waitcnt lgkmcnt(0)
	s_mul_i32 s0, s1, s0
	s_add_u32 s44, s88, 0x2e9d9300
	s_mul_i32 s0, s0, s2
	s_addc_u32 s45, s89, 0
	s_mov_b32 s1, 1
	s_branch .LBB0_1261

; #define RUN_PH(k) if (ph0 <= (k) && (k) < ph1) { if ((k) != ph0) xcd_barrier(xb); run_phase<(k)>(kp, shm); }
; __device__ __forceinline__ void xcd_barrier(const XcdBarrier& b) {
;     asm volatile("s_waitcnt vmcnt(0)" ::: "memory");
;     __syncthreads();
;     if (threadIdx.x == 0) {
;         unsigned* bar = b.bar;
;         __builtin_amdgcn_s_waitcnt(0);
;         unsigned nloc = b.st[0], nx = b.st[1];
;         if (nloc == 0u) { xcd_barrier_complete(bar, b.x, nloc, nx); b.st[0] = nloc; b.st[1] = nx; }
; __global__ void __launch_bounds__(512, 2) mega(Params P, int ph0, int ph1) {
;     ...
;     RUN_PH(0) RUN_PH(1) RUN_PH(2) RUN_PH(3) RUN_PH(4) RUN_PH(5) RUN_PH(6) RUN_PH(7) RUN_PH(8) RUN_PH(9)
;     RUN_PH(10) RUN_PH(11) RUN_PH(12) RUN_PH(13) RUN_PH(14) RUN_PH(15) RUN_PH(16) RUN_PH(17)
.LBB0_1327:
	s_cmp_gt_i32 s94, 14
	s_waitcnt lgkmcnt(0)
	s_cselect_b64 s[0:1], -1, 0
	s_cmp_lt_i32 s95, 15
	s_cselect_b64 s[2:3], -1, 0
	s_or_b64 s[0:1], s[0:1], s[2:3]
	s_and_b64 vcc, exec, s[0:1]
	s_cbranch_vccnz .LBB0_1420
	s_cmp_eq_u32 s94, 14
	s_cbranch_scc1 .LBB0_1382
	s_waitcnt vmcnt(0)
	s_waitcnt vmcnt(0)
	v_cmp_lt_u32_e32 vcc, 63, v0
	s_and_saveexec_b64 s[0:1], vcc
	s_getpc_b64 s[2:3]
	v_lshlrev_b32_e32 v1, 6, v0
	global_load_dword v1, v1, s[2:3] offset:-4096
	s_mov_b64 exec, s[0:1]
	s_nop 0
	s_barrier
	s_and_saveexec_b64 s[4:5], s[92:93]
	s_cbranch_execz .LBB0_1381
	v_mov_b32_e32 v1, 0
	s_waitcnt vmcnt(0) expcnt(0) lgkmcnt(0)
	ds_read_b32 v3, v1
	ds_read_b32 v2, v1 offset:4
	s_waitcnt lgkmcnt(1)
	v_cmp_ne_u32_e32 vcc, 0, v3
	s_cbranch_vccnz .LBB0_1345
	s_add_u32 s6, s88, 0x2e9d8200
	s_addc_u32 s7, s89, 0
	s_add_u32 s8, s88, 0x2e9d8400
	s_addc_u32 s9, s89, 0
	s_add_u32 s12, s88, 0x2e9d8500
	s_addc_u32 s13, s89, 0
	s_add_u32 s14, s88, 0x2e9d8600
	s_addc_u32 s15, s89, 0
	s_add_u32 s16, s88, 0x2e9d8700
	s_addc_u32 s17, s89, 0
	s_add_u32 s18, s88, 0x2e9d8800
	s_addc_u32 s19, s89, 0
	s_add_u32 s20, s88, 0x2e9d8900
	s_addc_u32 s21, s89, 0
	s_add_u32 s22, s88, 0x2e9d8a00
	s_addc_u32 s23, s89, 0
	s_add_u32 s24, s88, 0x2e9d8b00
	s_addc_u32 s25, s89, 0
	s_add_u32 s26, s88, 0x2e9d8c00
	s_addc_u32 s27, s89, 0
	s_add_u32 s28, s88, 0x2e9d8d00
	s_addc_u32 s29, s89, 0
	s_add_u32 s34, s88, 0x2e9d8e00
	s_addc_u32 s35, s89, 0
	s_add_u32 s36, s88, 0x2e9d8f00
	s_addc_u32 s37, s89, 0
	s_add_u32 s38, s88, 0x2e9d9000
	s_addc_u32 s39, s89, 0
	s_load_dwordx2 s[0:1], s[86:87], 0xe0
	s_load_dword s2, s[86:87], 0xe8
	s_add_u32 s40, s88, 0x2e9d9100
	s_addc_u32 s41, s89, 0
	s_add_u32 s42, s88, 0x2e9d9200
	s_addc_u32 s43, s89, 0
	s_waitcnt lgkmcnt(0)
	s_mul_i32 s0, s1, s0
	s_add_u32 s44, s88, 0x2e9d9300
	s_mul_i32 s0, s0, s2
	s_addc_u32 s45, s89, 0
	s_mov_b32 s1, 1
	s_branch .LBB0_1333

; #define RUN_PH(k) if (ph0 <= (k) && (k) < ph1) { if ((k) != ph0) xcd_barrier(xb); run_phase<(k)>(kp, shm); }
; __device__ __forceinline__ void xcd_barrier(const XcdBarrier& b) {
;     asm volatile("s_waitcnt vmcnt(0)" ::: "memory");
;     __syncthreads();
;     if (threadIdx.x == 0) {
;         unsigned* bar = b.bar;
;         __builtin_amdgcn_s_waitcnt(0);
;         unsigned nloc = b.st[0], nx = b.st[1];
;         if (nloc == 0u) { xcd_barrier_complete(bar, b.x, nloc, nx); b.st[0] = nloc; b.st[1] = nx; }
; __global__ void __launch_bounds__(512, 2) mega(Params P, int ph0, int ph1) {
;     ...
;     RUN_PH(0) RUN_PH(1) RUN_PH(2) RUN_PH(3) RUN_PH(4) RUN_PH(5) RUN_PH(6) RUN_PH(7) RUN_PH(8) RUN_PH(9)
;     RUN_PH(10) RUN_PH(11) RUN_PH(12) RUN_PH(13) RUN_PH(14) RUN_PH(15) RUN_PH(16) RUN_PH(17)
.LBB0_1420:
	s_cmp_gt_i32 s94, 15
	s_cselect_b64 s[0:1], -1, 0
	s_cmp_lt_i32 s95, 16
	s_cselect_b64 s[2:3], -1, 0
	s_or_b64 s[0:1], s[0:1], s[2:3]
	s_and_b64 vcc, exec, s[0:1]
	s_cbranch_vccnz .LBB0_1523
	s_cmp_eq_u32 s94, 15
	s_cbranch_scc1 .LBB0_1475
	s_waitcnt vmcnt(0)
	s_waitcnt vmcnt(0) lgkmcnt(0)
	v_cmp_lt_u32_e32 vcc, 63, v0
	s_and_saveexec_b64 s[0:1], vcc
	s_getpc_b64 s[2:3]
	v_lshlrev_b32_e32 v1, 6, v0
	global_load_dword v1, v1, s[2:3] offset:-4096
	s_mov_b64 exec, s[0:1]
	s_nop 0
	s_barrier
	s_and_saveexec_b64 s[4:5], s[92:93]
	s_cbranch_execz .LBB0_1474
	v_mov_b32_e32 v1, 0
	s_waitcnt vmcnt(0) expcnt(0) lgkmcnt(0)
	ds_read_b32 v3, v1
	ds_read_b32 v2, v1 offset:4
	s_waitcnt lgkmcnt(1)
	v_cmp_ne_u32_e32 vcc, 0, v3
	s_cbranch_vccnz .LBB0_1438
	s_add_u32 s6, s88, 0x2e9d8200
	s_addc_u32 s7, s89, 0
	s_add_u32 s8, s88, 0x2e9d8400
	s_addc_u32 s9, s89, 0
	s_add_u32 s12, s88, 0x2e9d8500
	s_addc_u32 s13, s89, 0
	s_add_u32 s14, s88, 0x2e9d8600
	s_addc_u32 s15, s89, 0
	s_add_u32 s16, s88, 0x2e9d8700
	s_addc_u32 s17, s89, 0
	s_add_u32 s18, s88, 0x2e9d8800
	s_addc_u32 s19, s89, 0
	s_add_u32 s20, s88, 0x2e9d8900
	s_addc_u32 s21, s89, 0
	s_add_u32 s22, s88, 0x2e9d8a00
	s_addc_u32 s23, s89, 0
	s_add_u32 s24, s88, 0x2e9d8b00
	s_addc_u32 s25, s89, 0
	s_add_u32 s26, s88, 0x2e9d8c00
	s_addc_u32 s27, s89, 0
	s_add_u32 s28, s88, 0x2e9d8d00
	s_addc_u32 s29, s89, 0
	s_add_u32 s34, s88, 0x2e9d8e00
	s_addc_u32 s35, s89, 0
	s_add_u32 s36, s88, 0x2e9d8f00
	s_addc_u32 s37, s89, 0
	s_add_u32 s38, s88, 0x2e9d9000
	s_addc_u32 s39, s89, 0
	s_load_dwordx2 s[0:1], s[86:87], 0xe0
	s_load_dword s2, s[86:87], 0xe8
	s_add_u32 s40, s88, 0x2e9d9100
	s_addc_u32 s41, s89, 0
	s_add_u32 s42, s88, 0x2e9d9200
	s_addc_u32 s43, s89, 0
	s_waitcnt lgkmcnt(0)
	s_mul_i32 s0, s1, s0
	s_add_u32 s44, s88, 0x2e9d9300
	s_mul_i32 s0, s0, s2
	s_addc_u32 s45, s89, 0
	s_mov_b32 s1, 1
	s_branch .LBB0_1426

; #define RUN_PH(k) if (ph0 <= (k) && (k) < ph1) { if ((k) != ph0) xcd_barrier(xb); run_phase<(k)>(kp, shm); }
; __device__ __forceinline__ void xcd_barrier(const XcdBarrier& b) {
;     asm volatile("s_waitcnt vmcnt(0)" ::: "memory");
;     __syncthreads();
;     if (threadIdx.x == 0) {
;         unsigned* bar = b.bar;
;         __builtin_amdgcn_s_waitcnt(0);
;         unsigned nloc = b.st[0], nx = b.st[1];
;         if (nloc == 0u) { xcd_barrier_complete(bar, b.x, nloc, nx); b.st[0] = nloc; b.st[1] = nx; }
; __global__ void __launch_bounds__(512, 2) mega(Params P, int ph0, int ph1) {
;     ...
;     RUN_PH(0) RUN_PH(1) RUN_PH(2) RUN_PH(3) RUN_PH(4) RUN_PH(5) RUN_PH(6) RUN_PH(7) RUN_PH(8) RUN_PH(9)
;     RUN_PH(10) RUN_PH(11) RUN_PH(12) RUN_PH(13) RUN_PH(14) RUN_PH(15) RUN_PH(16) RUN_PH(17)
.LBB0_1523:
	s_cmp_gt_i32 s94, 16
	s_cselect_b64 s[0:1], -1, 0
	s_cmp_lt_i32 s95, 17
	s_cselect_b64 s[2:3], -1, 0
	s_or_b64 s[0:1], s[0:1], s[2:3]
	s_and_b64 vcc, exec, s[0:1]
	s_cbranch_vccnz .LBB0_1598
	s_cmp_eq_u32 s94, 16
	s_cbranch_scc1 .LBB0_1578
	s_waitcnt vmcnt(0)
	s_waitcnt vmcnt(0) lgkmcnt(0)
	v_cmp_lt_u32_e32 vcc, 63, v0
	s_and_saveexec_b64 s[0:1], vcc
	s_getpc_b64 s[2:3]
	v_lshlrev_b32_e32 v1, 6, v0
	global_load_dword v1, v1, s[2:3] offset:-4096
	s_mov_b64 exec, s[0:1]
	s_nop 0
	s_barrier
	s_and_saveexec_b64 s[4:5], s[92:93]
	s_cbranch_execz .LBB0_1577
	v_mov_b32_e32 v1, 0
	s_waitcnt vmcnt(0) expcnt(0) lgkmcnt(0)
	ds_read_b32 v3, v1
	ds_read_b32 v2, v1 offset:4
	s_waitcnt lgkmcnt(1)
	v_cmp_ne_u32_e32 vcc, 0, v3
	s_cbranch_vccnz .LBB0_1541
	s_add_u32 s6, s88, 0x2e9d8200
	s_addc_u32 s7, s89, 0
	s_add_u32 s8, s88, 0x2e9d8400
	s_addc_u32 s9, s89, 0
	s_add_u32 s12, s88, 0x2e9d8500
	s_addc_u32 s13, s89, 0
	s_add_u32 s14, s88, 0x2e9d8600
	s_addc_u32 s15, s89, 0
	s_add_u32 s16, s88, 0x2e9d8700
	s_addc_u32 s17, s89, 0
	s_add_u32 s18, s88, 0x2e9d8800
	s_addc_u32 s19, s89, 0
	s_add_u32 s20, s88, 0x2e9d8900
	s_addc_u32 s21, s89, 0
	s_add_u32 s22, s88, 0x2e9d8a00
	s_addc_u32 s23, s89, 0
	s_add_u32 s24, s88, 0x2e9d8b00
	s_addc_u32 s25, s89, 0
	s_add_u32 s26, s88, 0x2e9d8c00
	s_addc_u32 s27, s89, 0
	s_add_u32 s28, s88, 0x2e9d8d00
	s_addc_u32 s29, s89, 0
	s_add_u32 s34, s88, 0x2e9d8e00
	s_addc_u32 s35, s89, 0
	s_add_u32 s36, s88, 0x2e9d8f00
	s_addc_u32 s37, s89, 0
	s_add_u32 s38, s88, 0x2e9d9000
	s_addc_u32 s39, s89, 0
	s_load_dwordx2 s[0:1], s[86:87], 0xe0
	s_load_dword s2, s[86:87], 0xe8
	s_add_u32 s40, s88, 0x2e9d9100
	s_addc_u32 s41, s89, 0
	s_add_u32 s42, s88, 0x2e9d9200
	s_addc_u32 s43, s89, 0
	s_waitcnt lgkmcnt(0)
	s_mul_i32 s0, s1, s0
	s_add_u32 s44, s88, 0x2e9d9300
	s_mul_i32 s0, s0, s2
	s_addc_u32 s45, s89, 0
	s_mov_b32 s1, 1
	s_branch .LBB0_1529

; #define RUN_PH(k) if (ph0 <= (k) && (k) < ph1) { if ((k) != ph0) xcd_barrier(xb); run_phase<(k)>(kp, shm); }
; __device__ __forceinline__ void xcd_barrier(const XcdBarrier& b) {
;     asm volatile("s_waitcnt vmcnt(0)" ::: "memory");
;     __syncthreads();
;     if (threadIdx.x == 0) {
;         unsigned* bar = b.bar;
;         __builtin_amdgcn_s_waitcnt(0);
;         unsigned nloc = b.st[0], nx = b.st[1];
;         if (nloc == 0u) { xcd_barrier_complete(bar, b.x, nloc, nx); b.st[0] = nloc; b.st[1] = nx; }
; __global__ void __launch_bounds__(512, 2) mega(Params P, int ph0, int ph1) {
;     ...
;     RUN_PH(0) RUN_PH(1) RUN_PH(2) RUN_PH(3) RUN_PH(4) RUN_PH(5) RUN_PH(6) RUN_PH(7) RUN_PH(8) RUN_PH(9)
;     RUN_PH(10) RUN_PH(11) RUN_PH(12) RUN_PH(13) RUN_PH(14) RUN_PH(15) RUN_PH(16) RUN_PH(17)
.LBB0_1598:
	s_cmp_gt_i32 s94, 17
	s_cselect_b64 s[0:1], -1, 0
	s_cmp_lt_i32 s95, 18
	s_cselect_b64 s[2:3], -1, 0
	s_or_b64 s[0:1], s[0:1], s[2:3]
	s_and_b64 vcc, exec, s[0:1]
	s_cbranch_vccnz .LBB0_1656
	s_cmp_eq_u32 s94, 17
	s_cbranch_scc1 .LBB0_1653
	s_waitcnt vmcnt(0)
	s_waitcnt vmcnt(0) lgkmcnt(0)
	v_cmp_lt_u32_e32 vcc, 63, v0
	s_and_saveexec_b64 s[0:1], vcc
	s_getpc_b64 s[2:3]
	v_lshlrev_b32_e32 v1, 6, v0
	global_load_dword v1, v1, s[2:3] offset:-4096
	s_mov_b64 exec, s[0:1]
	s_nop 0
	s_barrier
	s_and_saveexec_b64 s[4:5], s[92:93]
	s_cbranch_execz .LBB0_1652
	v_mov_b32_e32 v1, 0
	s_waitcnt vmcnt(0) expcnt(0) lgkmcnt(0)
	ds_read_b32 v3, v1
	ds_read_b32 v2, v1 offset:4
	s_waitcnt lgkmcnt(1)
	v_cmp_ne_u32_e32 vcc, 0, v3
	s_cbranch_vccnz .LBB0_1616
	s_add_u32 s6, s88, 0x2e9d8200
	s_addc_u32 s7, s89, 0
	s_add_u32 s8, s88, 0x2e9d8400
	s_addc_u32 s9, s89, 0
	s_add_u32 s12, s88, 0x2e9d8500
	s_addc_u32 s13, s89, 0
	s_add_u32 s14, s88, 0x2e9d8600
	s_addc_u32 s15, s89, 0
	s_add_u32 s16, s88, 0x2e9d8700
	s_addc_u32 s17, s89, 0
	s_add_u32 s18, s88, 0x2e9d8800
	s_addc_u32 s19, s89, 0
	s_add_u32 s20, s88, 0x2e9d8900
	s_addc_u32 s21, s89, 0
	s_add_u32 s22, s88, 0x2e9d8a00
	s_addc_u32 s23, s89, 0
	s_add_u32 s24, s88, 0x2e9d8b00
	s_addc_u32 s25, s89, 0
	s_add_u32 s26, s88, 0x2e9d8c00
	s_addc_u32 s27, s89, 0
	s_add_u32 s28, s88, 0x2e9d8d00
	s_addc_u32 s29, s89, 0
	s_add_u32 s30, s88, 0x2e9d8e00
	s_addc_u32 s31, s89, 0
	s_add_u32 s34, s88, 0x2e9d8f00
	s_addc_u32 s35, s89, 0
	s_add_u32 s36, s88, 0x2e9d9000
	s_addc_u32 s37, s89, 0
	s_load_dwordx2 s[0:1], s[86:87], 0xe0
	s_load_dword s2, s[86:87], 0xe8
	s_add_u32 s38, s88, 0x2e9d9100
	s_addc_u32 s39, s89, 0
	s_add_u32 s40, s88, 0x2e9d9200
	s_addc_u32 s41, s89, 0
	s_waitcnt lgkmcnt(0)
	s_mul_i32 s0, s1, s0
	s_add_u32 s42, s88, 0x2e9d9300
	s_mul_i32 s0, s0, s2
	s_addc_u32 s43, s89, 0
	s_mov_b32 s1, 1
	s_branch .LBB0_1604
